# same-XCC seams after P4/P6 use one arrive counter per XCD half (32 workgroups) instead of per quad
# baseline (speedup 1.0000x reference)
; #define LAS __attribute__((address_space(3)))
; __device__ __forceinline__ unsigned xb_add(unsigned* p, unsigned v) { return __hip_atomic_fetch_add(p, v, __ATOMIC_RELAXED, __HIP_MEMORY_SCOPE_AGENT); }
; __device__ __forceinline__ unsigned xb_xcc_id() { return (unsigned)__builtin_amdgcn_s_getreg((3 << 11) | 20) & 0xFu; }
; __device__ __forceinline__ XcdBarrier xcd_barrier_post(unsigned* bar, volatile LAS unsigned* st, unsigned gsize) {
;     XcdBarrier b; b.bar = bar; b.x = xb_xcc_id(); b.st = st; b.gsize = gsize;
;     if (threadIdx.x == 0) (void)xb_add(&bar[XB_XCNT(b.x)], 1u);
;     return b;
.LBB0_10:
	v_writelane_b32 v250, s10, 13
	s_or_b64 exec, exec, s[4:5]
	s_and_saveexec_b64 s[4:5], s[12:13]
	s_cbranch_execz .Lqx_post_done
	s_and_b32 s6, s2, 7
	s_lshl_b32 s6, s6, 2
	s_add_i32 s6, s6, 0x18000
	v_mov_b32_e32 v1, s6
	s_lshl_b32 s7, 1, s10
	v_mov_b32_e32 v2, s7
	global_atomic_or v1, v2, s[14:15]

; __global__ void __launch_bounds__(NWAVES * 64, 2) fwd(Args a) {
;     ...
;     XcdBarrier bar = xcd_barrier_post(ctl + CW_BAR, MISC + 8, (unsigned)G);
;     XcdBarrier barg = xcd_barrier_post(ctl + CW_GBAR + grp * XCD_BAR_WORDS, MISC + 12, (unsigned)gsz);
.LBB0_65:
	s_or_b64 exec, exec, s[4:5]
	s_and_saveexec_b64 s[4:5], s[80:81]
	s_cbranch_execz .Lqx_chk_done
	s_and_b32 s6, s101, 7
	s_lshl_b32 s6, s6, 2
	s_add_i32 s6, s6, 0x18000
	v_mov_b32_e32 v1, s6
	global_load_dword v2, v1, s[60:61] sc1
	s_waitcnt vmcnt(0)
	v_add_u32_e32 v3, -1, v2
	v_and_b32_e32 v3, v3, v2
	v_cmp_ne_u32_e32 vcc, 0, v3
	s_cbranch_vccz .Lqx_chk_done
	v_mov_b32_e32 v1, 0x18800
	v_mov_b32_e32 v2, 1
	global_atomic_add v1, v2, s[60:61]

; __device__ __forceinline__ unsigned xb_ld(unsigned* p)              { return __hip_atomic_load(p, __ATOMIC_RELAXED, __HIP_MEMORY_SCOPE_AGENT); }
; __device__ __forceinline__ unsigned xb_add(unsigned* p, unsigned v) { return __hip_atomic_fetch_add(p, v, __ATOMIC_RELAXED, __HIP_MEMORY_SCOPE_AGENT); }
; #define XB_SPIN(cond, bar) do { unsigned _sp = 0; while (cond) { __builtin_amdgcn_s_sleep(1); \
;     if ((++_sp & 255u) == 0u) { if (xb_ld(&(bar)[XB_TMO])) break; if (_sp > XB_SPIN_CAP) { atomicAdd(&(bar)[XB_TMO], 1u); break; } } } } while (0)
; __device__ __forceinline__ void xcd_barrier(const XcdBarrier& b) {
;     asm volatile("s_waitcnt vmcnt(0)" ::: "memory");
;     __syncthreads();
;     if (threadIdx.x == 0) {
;         unsigned* bar = b.bar;
;         __builtin_amdgcn_s_waitcnt(0);
;         unsigned nloc = b.st[0], nx = b.st[1];
;         if (nloc == 0u) { xcd_barrier_complete(bar, b.x, b.gsize, nloc, nx); b.st[0] = nloc; b.st[1] = nx; }
;         const unsigned old = xb_add(&bar[XB_XSUB(b.x)], 1u);
;         const unsigned gen = old / nloc;
;         if (old + 1u == (gen + 1u) * nloc) {
;             __builtin_amdgcn_fence(__ATOMIC_RELEASE, "agent");
;             asm volatile("s_waitcnt vmcnt(0)" ::: "memory");
;             const unsigned og = xb_add(&bar[XB_TOP], 1u);
;             const unsigned tg = og / nx;
;             if (og + 1u == (tg + 1u) * nx) xb_add(&bar[XB_TOPGEN], 1u);
;             else XB_SPIN(xb_ld(&bar[XB_TOPGEN]) == tg, bar);
;             __builtin_amdgcn_fence(__ATOMIC_ACQUIRE, "agent");
;             xb_add(&bar[XB_XGEN(b.x)], 1u);
;             asm volatile("s_waitcnt vmcnt(0)" ::: "memory");
;         } else {
;             XB_SPIN(xb_ld(&bar[XB_XGEN(b.x)]) == gen, bar);
;             __builtin_amdgcn_fence(__ATOMIC_ACQUIRE, "agent");
;             asm volatile("s_waitcnt vmcnt(0)" ::: "memory");
;         }
;     }
;     __syncthreads();
; }
.LBB0_457:
	s_waitcnt vmcnt(0)
	s_barrier
	s_and_saveexec_b64 s[0:1], s[90:91]
	s_xor_b64 s[0:1], exec, s[0:1]
	s_cbranch_execz .LBB0_510
	s_cmp_lg_u32 s100, 0
	s_cbranch_scc1 .Lq4_slow
	v_readlane_b32 s4, v250, 14
	v_readlane_b32 s5, v250, 15
	s_and_b32 s6, s101, 7
	s_lshl_b32 s6, s6, 7
	s_add_i32 s6, s6, 0x19000
	v_mov_b32_e32 v1, s6
	v_mov_b32_e32 v2, 1
	s_mov_b32 s7, 0
	s_nop 4
	global_atomic_add v1, v2, s[4:5]
	buffer_inv sc1
.Lq4_spin:
	global_load_dword v3, v1, s[4:5] sc1
	s_waitcnt vmcnt(0)
	v_cmp_gt_u32_e32 vcc, 32, v3
	s_cbranch_vccz .Lq4_ok
	s_sleep 1
	s_add_i32 s7, s7, 1
	s_cmp_lt_u32 s7, 0x8000
	s_cbranch_scc1 .Lq4_spin

; __device__ __forceinline__ unsigned xb_ld(unsigned* p)              { return __hip_atomic_load(p, __ATOMIC_RELAXED, __HIP_MEMORY_SCOPE_AGENT); }
; __device__ __forceinline__ unsigned xb_add(unsigned* p, unsigned v) { return __hip_atomic_fetch_add(p, v, __ATOMIC_RELAXED, __HIP_MEMORY_SCOPE_AGENT); }
; #define XB_SPIN(cond, bar) do { unsigned _sp = 0; while (cond) { __builtin_amdgcn_s_sleep(1); \
;     if ((++_sp & 255u) == 0u) { if (xb_ld(&(bar)[XB_TMO])) break; if (_sp > XB_SPIN_CAP) { atomicAdd(&(bar)[XB_TMO], 1u); break; } } } } while (0)
; __device__ __forceinline__ void xcd_barrier(const XcdBarrier& b) {
;     asm volatile("s_waitcnt vmcnt(0)" ::: "memory");
;     __syncthreads();
;     if (threadIdx.x == 0) {
;         unsigned* bar = b.bar;
;         __builtin_amdgcn_s_waitcnt(0);
;         unsigned nloc = b.st[0], nx = b.st[1];
;         if (nloc == 0u) { xcd_barrier_complete(bar, b.x, b.gsize, nloc, nx); b.st[0] = nloc; b.st[1] = nx; }
;         const unsigned old = xb_add(&bar[XB_XSUB(b.x)], 1u);
;         const unsigned gen = old / nloc;
;         if (old + 1u == (gen + 1u) * nloc) {
;             __builtin_amdgcn_fence(__ATOMIC_RELEASE, "agent");
;             asm volatile("s_waitcnt vmcnt(0)" ::: "memory");
;             const unsigned og = xb_add(&bar[XB_TOP], 1u);
;             const unsigned tg = og / nx;
;             if (og + 1u == (tg + 1u) * nx) xb_add(&bar[XB_TOPGEN], 1u);
;             else XB_SPIN(xb_ld(&bar[XB_TOPGEN]) == tg, bar);
;             __builtin_amdgcn_fence(__ATOMIC_ACQUIRE, "agent");
;             xb_add(&bar[XB_XGEN(b.x)], 1u);
;             asm volatile("s_waitcnt vmcnt(0)" ::: "memory");
;         } else {
;             XB_SPIN(xb_ld(&bar[XB_XGEN(b.x)]) == gen, bar);
;             __builtin_amdgcn_fence(__ATOMIC_ACQUIRE, "agent");
;             asm volatile("s_waitcnt vmcnt(0)" ::: "memory");
;         }
;     }
;     __syncthreads();
; }
.LBB0_638:
	s_or_b64 exec, exec, s[4:5]
	s_waitcnt vmcnt(0)
	s_barrier
	s_and_saveexec_b64 s[0:1], s[90:91]
	v_readlane_b32 s62, v250, 42
	v_readlane_b32 s64, v250, 40
	v_readlane_b32 s63, v250, 43
	v_readlane_b32 s65, v250, 41
	s_cbranch_execz .LBB0_690
	s_cmp_lg_u32 s100, 0
	s_cbranch_scc1 .Lq6_slow
	v_readlane_b32 s4, v250, 14
	v_readlane_b32 s5, v250, 15
	s_and_b32 s6, s101, 7
	s_lshl_b32 s6, s6, 7
	s_add_i32 s6, s6, 0x1b000
	v_mov_b32_e32 v1, s6
	v_mov_b32_e32 v2, 1
	s_mov_b32 s7, 0
	s_nop 4
	global_atomic_add v1, v2, s[4:5]
	buffer_inv sc1
